# gate-up phases: workgroups start in 4 groups (blockIdx&3) staggered by ~1.6us so epilogue store bursts do not coincide chip-wide; on top of v6
# speedup vs baseline: 1.0035x; 1.0035x over previous
; #define PG8_STAGE(bufoff, gbase, voff) do { _Pragma("unroll") for (int _i = 0; _i < 2; ++_i) \
;         __builtin_amdgcn_global_load_lds((const unsigned*)((const char*)(gbase) + (voff)[_i]), (PG8_LAS unsigned*)(lds + (bufoff) + ldsw + _i * 8192), 16, 0, 0); } while (0)
; #define PG8_WAIT_V(n) asm volatile("s_waitcnt vmcnt(" #n ")" ::: "memory")
; #define PG8_BAR __builtin_amdgcn_s_barrier()
; template <class Epi, class Sched, bool ALIGN_EPI = false, bool SP2 = false>
; __device__ __forceinline__ void gemm_phase(PG8_LAS unsigned char* lds, const Gemm g, const Sched& S, const Epi& E) {
;     ...
;     if constexpr (SP2) {
;         PG8_STAGE(PG8_SB(0, 0), cB, voffB); PG8_STAGE(PG8_SB(0, 1), cB + hstep, voffB); PG8_STAGE(PG8_SA(0, 0), cA, voffA); PG8_STAGE(PG8_SA(0, 1), cA + hstep, voffA);
;         if (wr == 1) PG8_BAR;
;         PG8_WAIT_V(2); PG8_BAR;
;         PG8_STAGE(PG8_SB(1, 0), cB + kstep, voffB); PG8_STAGE(PG8_SA(1, 0), cA + kstep, voffA); PG8_STAGE(PG8_SB(1, 1), cB + hstep + kstep, voffB);
;         PG8_WAIT_V(6); PG8_BAR;
;     } else {
;         PG8_STAGE(PG8_SB(0, 0), cB, voffB); PG8_STAGE(PG8_SA(0, 0), cA, voffA); PG8_STAGE(PG8_SB(0, 1), cB + hstep, voffB); PG8_STAGE(PG8_SA(0, 1), cA + hstep, voffA);
;         if (wr == 1) PG8_BAR;
;         PG8_WAIT_V(4); PG8_BAR;
;         PG8_STAGE(PG8_SB(1, 0), cB + kstep, voffB); PG8_STAGE(PG8_SA(1, 0), cA + kstep, voffA); PG8_STAGE(PG8_SB(1, 1), cB + hstep + kstep, voffB);
;         PG8_WAIT_V(6); PG8_BAR;
;     }
;     for (;;) {
.LBB0_41:
	v_bfe_u32 v185, v16, 4, 2
	v_and_b32_e32 v184, 15, v16
	v_lshlrev_b32_e32 v17, 4, v185
	v_lshlrev_b32_e32 v16, 2, v16
	v_lshl_or_b32 v17, v184, 6, v17
	s_lshl_b32 s1, s38, 13
	v_and_b32_e32 v16, 32, v16
	s_waitcnt lgkmcnt(0)
	v_bitop3_b32 v18, v17, s1, v16 bitop3:0xde
	s_lshl_b32 s1, s23, 5
	s_and_b32 s1, s1, 0x60
	s_add_i32 m0, s43, 0x18000
	v_lshl_add_u64 v[8:9], v[8:9], 0, s[26:27]
	s_lshl_b32 s68, s38, 6
	s_lshl_b32 s23, s1, 7
	s_waitcnt vmcnt(2)
	s_barrier
	global_load_lds_dwordx4 v[8:9], off
	v_lshl_add_u64 v[6:7], v[6:7], 0, s[26:27]
	s_add_i32 m0, s43, 0x1a000
	s_add_i32 s69, s43, 0x8000
	s_add_i32 s72, s43, 0xa000
	global_load_lds_dwordx4 v[6:7], off
	v_lshl_add_u64 v[2:3], v[2:3], 0, s[26:27]
	s_mov_b32 m0, s69
	s_add_u32 s30, s36, 0x40080
	global_load_lds_dwordx4 v[2:3], off
	v_lshl_add_u64 v[2:3], v[4:5], 0, s[26:27]
	s_mov_b32 m0, s72
	s_addc_u32 s31, s37, 0
	global_load_lds_dwordx4 v[2:3], off
	s_add_i32 m0, s43, 0x1c000
	v_lshl_add_u64 v[2:3], s[30:31], 0, v[0:1]
	global_load_lds_dwordx4 v[2:3], off
	v_lshl_add_u64 v[2:3], s[30:31], 0, v[162:163]
	s_add_i32 m0, s43, 0x1e000
	s_cmpk_lt_u32 s21, 0x100
	global_load_lds_dwordx4 v[2:3], off
	v_lshlrev_b32_e32 v2, 14, v13
	v_and_b32_e32 v2, 0xffff8000, v2
	v_lshl_add_u32 v2, v14, 11, v2
	v_and_b32_e32 v3, 1, v13
	v_lshl_or_b32 v2, v3, 6, v2
	v_lshl_add_u32 v164, v15, 1, v2
	v_lshlrev_b32_e32 v2, 14, v10
	v_and_b32_e32 v2, 0xffff8000, v2
	s_waitcnt vmcnt(6)
	v_lshl_add_u32 v2, v11, 11, v2
	v_and_b32_e32 v3, 1, v10
	v_lshl_or_b32 v2, v3, 6, v2
	s_sext_i32_i16 s44, s24
	v_bitop3_b32 v186, v17, s23, v16 bitop3:0xde
	s_cselect_b64 s[50:51], -1, 0
	s_ashr_i32 s73, s67, 31
	s_mov_b32 s41, s25
	v_mov_b32_e32 v165, v1
	v_lshl_add_u32 v166, v12, 1, v2
	v_mov_b32_e32 v167, v1
	s_mov_b32 s92, 0
	s_lshl_b32 s24, s1, 1
	v_add_u32_e32 v187, 0, v18
	s_barrier
	v_readlane_b32 s52, v253, 0
	s_nop 3
	s_and_b32 s52, s52, 3
	s_cbranch_scc0 .Lgu_stag_done
.Lgu_stag:
	s_sleep 50
	s_add_i32 s52, s52, -1
	s_cmp_lg_u32 s52, 0
	s_cbranch_scc1 .Lgu_stag
.Lgu_stag_done:
	s_branch .LBB0_44
.LBB0_42:
	s_mov_b64 s[0:1], 0
